# attention: next item's Q fragments prefetched right behind its K-tile loads (v[220:251]) and moved into place at the loop top; first item via the prologue prefetch; STOREK ladder +8
# baseline (speedup 1.0000x reference)
.LBB0_1129:
	v_add_co_u32_e32 v20, vcc, s21, v16
	s_not_b32 s63, s14
	s_nop 0
	v_addc_co_u32_e32 v21, vcc, 0, v17, vcc
	v_add_co_u32_e32 v24, vcc, s22, v16
	v_readlane_b32 s10, v254, 49
	s_nop 0
	v_addc_co_u32_e32 v25, vcc, 0, v17, vcc
	v_add_co_u32_e32 v28, vcc, s23, v16
	global_load_dwordx4 v[20:23], v[20:21], off
	s_nop 0
	global_load_dwordx4 v[24:27], v[24:25], off
	v_addc_co_u32_e32 v29, vcc, 0, v17, vcc
	v_add_co_u32_e32 v32, vcc, s24, v16
	s_movk_i32 s14, 0xf0
	s_nop 0
	v_addc_co_u32_e32 v33, vcc, 0, v17, vcc
	v_add_co_u32_e32 v36, vcc, s15, v16
	global_load_dwordx4 v[28:31], v[28:29], off
	s_nop 0
	global_load_dwordx4 v[32:35], v[32:33], off
	v_addc_co_u32_e32 v37, vcc, 0, v17, vcc
	v_add_co_u32_e32 v40, vcc, s18, v16
	v_readlane_b32 s11, v254, 50
	s_nop 0
	v_addc_co_u32_e32 v41, vcc, 0, v17, vcc
	v_add_co_u32_e32 v44, vcc, s19, v16
	global_load_dwordx4 v[36:39], v[36:37], off
	s_nop 0
	global_load_dwordx4 v[40:43], v[40:41], off
	v_addc_co_u32_e32 v45, vcc, 0, v17, vcc
	v_add_co_u32_e32 v16, vcc, s20, v16
	s_and_b64 s[10:11], s[10:11], exec
	s_nop 0
	v_addc_co_u32_e32 v17, vcc, 0, v17, vcc
	global_load_dwordx4 v[44:47], v[44:45], off
	s_nop 0
	global_load_dwordx4 v[48:51], v[16:17], off
	v_xor_b32_e32 v16, v128, v19
	v_lshlrev_b32_e32 v17, 8, v128
	v_lshlrev_b32_e32 v54, 4, v16
	v_and_or_b32 v17, v54, s14, v17
	s_load_dwordx2 s[14:15], s[8:9], 0x70
	s_cselect_b32 s10, 0, 8
	s_lshl_b32 s11, 1, s40
	s_add_u32 s20, s4, s13
	s_addc_u32 s21, s5, 0
	s_waitcnt lgkmcnt(0)
	s_add_u32 s22, s14, 0x1100000
	v_cvt_f32_u32_e32 v152, s11
	s_addc_u32 s23, s15, 0
	s_lshl_b32 s11, s12, 4
	v_and_b32_e32 v149, 63, v19
	s_or_b32 s11, s11, 1
	s_cmp_gt_i32 s28, 0
	v_cmp_gt_u32_e64 s[42:43], 32, v149
	s_cselect_b64 s[24:25], -1, 0
	s_add_i32 s18, s40, 13
	s_and_b64 s[26:27], s[0:1], s[42:43]
	s_cmp_gt_i32 s28, 1
	s_cselect_b64 s[28:29], -1, 0
	s_add_i32 s0, s40, 12
	s_lshl_b64 s[60:61], 1, s0
	v_writelane_b32 v254, s60, 52
	v_bfe_u32 v53, v19, 5, 1
	v_and_b32_e32 v150, 31, v19
	v_writelane_b32 v254, s61, 53
	s_lshl_b64 s[60:61], 2, s0
	v_writelane_b32 v254, s60, 54
	v_ashrrev_i32_e32 v130, 2, v19
	v_lshlrev_b32_e32 v19, 4, v19
	v_lshlrev_b32_e32 v138, 4, v53
	v_writelane_b32 v254, s61, 55
	s_lshl_b64 s[60:61], 3, s0
	v_and_b32_e32 v16, 48, v19
	v_add_u32_e32 v151, 0, v17
	v_lshl_add_u64 v[132:133], s[6:7], 0, v[138:139]
	v_readlane_b32 s6, v253, 56
	v_mov_b32_e32 v17, v139
	v_writelane_b32 v254, s60, 56
	s_ashr_i32 s98, s58, 6
	s_ashr_i32 s99, s98, 31
	s_lshl_b64 s[98:99], s[98:99], 14
	s_and_b32 s100, s58, 63
	s_lshr_b32 s101, s100, s62
	s_mul_i32 s101, s101, s41
	s_add_u32 s98, s98, s101
	s_addc_u32 s99, s99, 0
	s_and_b32 s100, s100, s63
	s_lshl_b32 s100, s100, 8
	v_readlane_b32 s101, v253, 56
	v_mov_b32_e32 v219, 0
	s_nop 1
	s_add_i32 s100, s100, s101
	v_or_b32_e32 v218, s100, v150
	v_lshl_add_u64 v[218:219], s[98:99], 0, v[218:219]
	v_lshlrev_b64 v[218:219], 8, v[218:219]
	v_lshl_add_u64 v[218:219], v[132:133], 0, v[218:219]
	global_load_dwordx4 v[220:223], v[218:219], off
	global_load_dwordx4 v[224:227], v[218:219], off offset:32
	global_load_dwordx4 v[228:231], v[218:219], off offset:64
	global_load_dwordx4 v[232:235], v[218:219], off offset:96
	global_load_dwordx4 v[236:239], v[218:219], off offset:128
	global_load_dwordx4 v[240:243], v[218:219], off offset:160
	global_load_dwordx4 v[244:247], v[218:219], off offset:192
	global_load_dwordx4 v[248:251], v[218:219], off offset:224
	s_waitcnt vmcnt(16)
	ds_write_b128 v151, v[0:3]
	ds_write_b128 v151, v[8:11] offset:8192
	ds_write_b128 v151, v[4:7] offset:16384
	ds_write_b128 v151, v[12:15] offset:24576
	v_or_b32_e32 v2, s6, v150
	v_lshl_add_u64 v[0:1], s[14:15], 0, v[16:17]
	s_mov_b64 s[6:7], 0xc000000
	v_readlane_b32 s1, v253, 51
	v_writelane_b32 v254, s61, 57
	s_lshl_b64 s[60:61], 4, s0
	v_lshl_add_u64 v[134:135], v[0:1], 0, s[6:7]
	v_mov_b32_e32 v0, s1
	s_movk_i32 s1, 0x210
	v_writelane_b32 v254, s60, 58
	v_lshlrev_b32_e32 v52, 3, v18
	v_mad_u32_u24 v4, v150, s1, v0
	v_readlane_b32 s1, v253, 47
	v_writelane_b32 v254, s61, 59
	s_lshl_b64 s[60:61], 5, s0
	s_movk_i32 s50, 0x310
	v_lshl_add_u32 v160, v150, 2, s1
	v_lshlrev_b32_e32 v0, 1, v52
	v_mov_b32_e32 v1, v139
	v_readlane_b32 s1, v253, 53
	v_writelane_b32 v254, s60, 60
	v_mul_lo_u32 v55, v130, s50
	v_lshl_add_u64 v[136:137], s[4:5], 0, v[0:1]
	v_lshl_add_u32 v0, v2, 8, 0
	v_xor_b32_e32 v1, v53, v18
	v_bitop3_b32 v2, v53, v18, 2 bitop3:0x36
	v_bitop3_b32 v5, v53, v18, 4 bitop3:0x36
	v_bitop3_b32 v6, v53, v18, 6 bitop3:0x36
	v_bitop3_b32 v7, v53, v18, 8 bitop3:0x36
	v_bitop3_b32 v8, v53, v18, 10 bitop3:0x36
	v_bitop3_b32 v9, v53, v18, 12 bitop3:0x36
	v_bitop3_b32 v10, v53, v18, 14 bitop3:0x36
	v_add_u32_e32 v12, s1, v138
	v_writelane_b32 v254, s61, 61
	s_lshl_b64 s[60:61], 6, s0
	s_lshl_b64 s[0:1], 7, s0
	v_or_b32_e32 v19, 0x80, v150
	v_lshlrev_b32_e32 v157, 2, v53
	v_add_u32_e32 v3, 0, v55
	v_lshlrev_b32_e32 v1, 4, v1
	v_lshlrev_b32_e32 v2, 4, v2
	v_lshlrev_b32_e32 v5, 4, v5
	v_lshlrev_b32_e32 v6, 4, v6
	v_lshlrev_b32_e32 v7, 4, v7
	v_lshlrev_b32_e32 v8, 4, v8
	v_lshlrev_b32_e32 v9, 4, v9
	v_lshlrev_b32_e32 v10, 4, v10
	s_lshl_b64 s[4:5], 32, s53
	s_lshl_b64 s[12:13], 64, s53
	s_lshl_b64 s[14:15], 0x60, s53
	s_lshl_b64 s[44:45], 0x80, s53
	s_lshl_b64 s[46:47], 0xa0, s53
	s_lshl_b64 s[48:49], 0xc0, s53
	s_lshl_b64 s[72:73], 0xe0, s53
	s_lshl_b64 s[74:75], 0x100, s53
	s_lshl_b64 s[76:77], 0x120, s53
	s_lshl_b64 s[78:79], 0x140, s53
	s_lshl_b64 s[80:81], 0x160, s53
	v_mul_u32_u24_e32 v11, 0x310, v150
	v_mad_u32_u24 v13, v150, s50, v174
	v_writelane_b32 v254, s60, 62
	v_writelane_b32 v255, s0, 0
	s_mov_b32 s51, 0x16000
	v_add_u32_e32 v153, 0x10000, v151
	v_add_u32_e32 v154, 0x12000, v151
	v_add_u32_e32 v155, 0x14000, v151
	v_add_u32_e32 v156, 0x16000, v151
	v_sub_u32_e32 v158, v19, v157
	v_cvt_f32_ubyte0_e32 v159, v157
	v_ashrrev_i32_e32 v131, 31, v130
	s_lshl_b64 s[30:31], 1, s18
	s_lshl_b64 s[54:55], 2, s18
	s_lshl_b64 s[34:35], 3, s18
	s_lshl_b64 s[36:37], 4, s18
	s_lshl_b64 s[38:39], 5, s18
	s_lshl_b64 s[6:7], 6, s18
	s_lshl_b64 s[18:19], 7, s18
	v_writelane_b32 v254, s61, 63
	v_writelane_b32 v255, s1, 1
	s_lshl_b64 s[0:1], 0x2000, s40
	s_lshl_b32 s60, s4, 1
	s_lshl_b32 s64, s12, 1
	s_lshl_b32 s66, s14, 1
	s_lshl_b32 s56, s44, 1
	s_lshl_b32 s68, s46, 1
	s_lshl_b32 s70, s48, 1
	s_lshl_b32 s72, s72, 1
	s_lshl_b32 s74, s74, 1
	s_lshl_b32 s76, s76, 1
	s_lshl_b32 s78, s78, 1
	s_lshl_b32 s80, s80, 1
	v_add_u32_e32 v161, v3, v16
	v_add_u32_e32 v162, v4, v138
	v_add_u32_e32 v163, v0, v1
	v_add_u32_e32 v164, v0, v2
	v_add_u32_e32 v165, v0, v5
	v_add_u32_e32 v166, v0, v6
	v_add_u32_e32 v167, v0, v7
	v_add_u32_e32 v168, v0, v8
	v_add_u32_e32 v169, v0, v9
	v_add_u32_e32 v170, v0, v10
	v_add_u32_e32 v171, v12, v11
	v_add_u32_e32 v191, v12, v13
	s_lshl_b64 s[82:83], 0x4000, s40
	s_lshl_b64 s[84:85], 0x6000, s40
	s_lshl_b64 s[86:87], 0x8000, s40
	s_lshl_b64 s[88:89], 0xa000, s40
	s_lshl_b64 s[90:91], 0xc000, s40
	s_lshl_b64 s[92:93], 0xe000, s40
	s_waitcnt vmcnt(15)
	ds_write_b128 v151, v[20:23] offset:32768
	s_waitcnt vmcnt(14)
	ds_write_b128 v151, v[24:27] offset:40960
	s_waitcnt vmcnt(13)
	ds_write_b128 v151, v[28:31] offset:49152
	s_waitcnt vmcnt(12)
	ds_write_b128 v151, v[32:35] offset:57344
	s_waitcnt vmcnt(11)
	ds_write_b128 v153, v[36:39]
	s_waitcnt vmcnt(10)
	ds_write_b128 v154, v[40:43]
	s_waitcnt vmcnt(9)
	ds_write_b128 v155, v[44:47]
	s_waitcnt vmcnt(8)
	ds_write_b128 v156, v[48:51]
	v_mov_b32_e32 v178, v36
	v_mov_b32_e32 v179, v37
	v_mov_b32_e32 v180, v38
	v_mov_b32_e32 v181, v39
	v_mov_b32_e32 v182, v40
	v_mov_b32_e32 v183, v41
	v_mov_b32_e32 v184, v42
	v_mov_b32_e32 v185, v43
	v_mov_b32_e32 v186, v44
	v_mov_b32_e32 v187, v45
	v_mov_b32_e32 v188, v46
	v_mov_b32_e32 v189, v47
	v_mov_b32_e32 v190, v48
	v_mov_b32_e32 v172, v49
	v_mov_b32_e32 v173, v50
	v_mov_b32_e32 v174, v51

.LBB0_1131:
	s_ashr_i32 s44, s58, 6
	s_and_b32 s4, s58, 63
	s_add_i32 s46, s44, s10
	s_lshr_b32 s47, s4, s62
	s_and_b32 s5, s4, s63
	s_add_i32 s4, s11, s46
	s_waitcnt vmcnt(16)
	v_cvt_f32_i32_e32 v0, s4
	s_lshl_b32 s61, s5, 8
	v_readlane_b32 s4, v253, 56
	s_ashr_i32 s45, s44, 31
	v_mul_f32_e32 v0, 0xbe2aaaab, v0
	v_exp_f32_e32 v0, v0
	s_add_i32 s4, s61, s4
	s_lshl_b64 s[12:13], s[44:45], 14
	s_mul_i32 s45, s47, s41
	s_add_u32 s12, s12, s45
	v_or_b32_e32 v138, s4, v150
	s_addc_u32 s13, s13, 0
	v_mul_f32_e32 v2, v0, v152
	v_lshl_add_u64 v[0:1], s[12:13], 0, v[138:139]
	v_lshlrev_b64 v[0:1], 8, v[0:1]
	s_waitcnt vmcnt(8)
	v_mov_b32_e32 v93, v158
	v_lshl_add_u64 v[0:1], v[132:133], 0, v[0:1]
	v_mov_b32_e32 v44, v220
	v_mov_b32_e32 v45, v221
	v_mov_b32_e32 v46, v222
	v_mov_b32_e32 v47, v223
	v_mov_b32_e32 v40, v224
	v_mov_b32_e32 v41, v225
	v_mov_b32_e32 v42, v226
	v_mov_b32_e32 v43, v227
	v_mov_b32_e32 v36, v228
	v_mov_b32_e32 v37, v229
	v_mov_b32_e32 v38, v230
	v_mov_b32_e32 v39, v231
	v_mov_b32_e32 v32, v232
	v_mov_b32_e32 v33, v233
	v_mov_b32_e32 v34, v234
	v_mov_b32_e32 v35, v235
	v_mov_b32_e32 v28, v236
	v_mov_b32_e32 v29, v237
	v_mov_b32_e32 v30, v238
	v_mov_b32_e32 v31, v239
	v_mov_b32_e32 v24, v240
	v_mov_b32_e32 v25, v241
	v_mov_b32_e32 v26, v242
	v_mov_b32_e32 v27, v243
	v_mov_b32_e32 v20, v244
	v_mov_b32_e32 v21, v245
	v_mov_b32_e32 v22, v246
	v_mov_b32_e32 v23, v247
	v_mov_b32_e32 v16, v248
	v_mov_b32_e32 v17, v249
	v_mov_b32_e32 v18, v250
	v_mov_b32_e32 v19, v251

.LBB0_1210:
	v_add_co_u32_e32 v16, vcc, 0x8000, v40
	s_mov_b32 s4, 0x10000
	s_nop 0
	v_addc_co_u32_e32 v17, vcc, 0, v41, vcc
	v_add_co_u32_e32 v20, vcc, 0xa000, v40
	s_nop 1
	v_addc_co_u32_e32 v21, vcc, 0, v41, vcc
	v_add_co_u32_e32 v24, vcc, 0xc000, v40
	global_load_dwordx4 v[16:19], v[16:17], off
	s_nop 0
	global_load_dwordx4 v[20:23], v[20:21], off
	v_addc_co_u32_e32 v25, vcc, 0, v41, vcc
	v_add_co_u32_e32 v28, vcc, 0xe000, v40
	s_nop 1
	v_addc_co_u32_e32 v29, vcc, 0, v41, vcc
	v_add_co_u32_e32 v32, vcc, s4, v40
	s_mov_b32 s4, 0x12000
	s_nop 0
	v_addc_co_u32_e32 v33, vcc, 0, v41, vcc
	v_add_co_u32_e32 v36, vcc, s4, v40
	s_mov_b32 s4, 0x14000
	s_nop 0
	v_addc_co_u32_e32 v37, vcc, 0, v41, vcc
	v_add_co_u32_e32 v42, vcc, s4, v40
	global_load_dwordx4 v[24:27], v[24:25], off
	s_nop 0
	global_load_dwordx4 v[28:31], v[28:29], off
	v_addc_co_u32_e32 v43, vcc, 0, v41, vcc
	v_add_co_u32_e32 v44, vcc, s51, v40
	global_load_dwordx4 v[32:35], v[32:33], off
	s_nop 0
	global_load_dwordx4 v[36:39], v[36:37], off
	v_addc_co_u32_e32 v45, vcc, 0, v41, vcc
	global_load_dwordx4 v[40:43], v[42:43], off
	s_nop 0
	global_load_dwordx4 v[44:47], v[44:45], off
	s_ashr_i32 s98, s58, 6
	s_ashr_i32 s99, s98, 31
	s_lshl_b64 s[98:99], s[98:99], 14
	s_and_b32 s100, s58, 63
	s_lshr_b32 s101, s100, s62
	s_mul_i32 s101, s101, s41
	s_add_u32 s98, s98, s101
	s_addc_u32 s99, s99, 0
	s_and_b32 s100, s100, s63
	s_lshl_b32 s100, s100, 8
	v_readlane_b32 s101, v253, 56
	v_mov_b32_e32 v219, 0
	s_nop 1
	s_add_i32 s100, s100, s101
	v_or_b32_e32 v218, s100, v150
	v_lshl_add_u64 v[218:219], s[98:99], 0, v[218:219]
	v_lshlrev_b64 v[218:219], 8, v[218:219]
	v_lshl_add_u64 v[218:219], v[132:133], 0, v[218:219]
	global_load_dwordx4 v[220:223], v[218:219], off
	global_load_dwordx4 v[224:227], v[218:219], off offset:32
	global_load_dwordx4 v[228:231], v[218:219], off offset:64
	global_load_dwordx4 v[232:235], v[218:219], off offset:96
	global_load_dwordx4 v[236:239], v[218:219], off offset:128
	global_load_dwordx4 v[240:243], v[218:219], off offset:160
	global_load_dwordx4 v[244:247], v[218:219], off offset:192
	global_load_dwordx4 v[248:251], v[218:219], off offset:224

.LBB0_1243:
	s_waitcnt lgkmcnt(1)
	v_cvt_pk_bf16_f32 v52, v52, v53
	v_cvt_pk_bf16_f32 v53, v54, v55
	s_waitcnt lgkmcnt(0)
	v_cvt_pk_bf16_f32 v54, v48, v49
	v_cvt_pk_bf16_f32 v55, v50, v51
	v_lshl_add_u64 v[48:49], s[92:93], 1, v[142:143]
	s_mov_b64 s[12:13], -1
	s_and_b64 vcc, exec, s[94:95]
	global_store_dwordx4 v[48:49], v[52:55], off sc1
	s_barrier
	s_cbranch_vccz .LBB0_1130
	s_waitcnt vmcnt(24)
	ds_write_b128 v151, v[0:3]
	ds_write_b128 v151, v[8:11] offset:8192
	ds_write_b128 v151, v[4:7] offset:16384
	ds_write_b128 v151, v[12:15] offset:24576
	s_waitcnt vmcnt(23)
	ds_write_b128 v151, v[16:19] offset:32768
	s_waitcnt vmcnt(22)
	ds_write_b128 v151, v[20:23] offset:40960
	s_waitcnt vmcnt(21)
	ds_write_b128 v151, v[24:27] offset:49152
	s_waitcnt vmcnt(20)
	ds_write_b128 v151, v[28:31] offset:57344
	s_waitcnt vmcnt(19)
	ds_write_b128 v153, v[32:35]
	s_waitcnt vmcnt(18)
	ds_write_b128 v154, v[36:39]
	s_waitcnt vmcnt(17)
	ds_write_b128 v155, v[40:43]
	s_waitcnt vmcnt(16)
	ds_write_b128 v156, v[44:47]
	v_mov_b32_e32 v178, v32
	v_mov_b32_e32 v179, v33
	v_mov_b32_e32 v180, v34
	v_mov_b32_e32 v181, v35
	v_mov_b32_e32 v182, v36
	v_mov_b32_e32 v183, v37
	v_mov_b32_e32 v184, v38
	v_mov_b32_e32 v185, v39
	v_mov_b32_e32 v186, v40
	v_mov_b32_e32 v187, v41
	v_mov_b32_e32 v188, v42
	v_mov_b32_e32 v189, v43
	v_mov_b32_e32 v190, v44
	v_mov_b32_e32 v172, v45
	v_mov_b32_e32 v173, v46
	v_mov_b32_e32 v174, v47
	s_mov_b64 s[12:13], 0
	s_branch .LBB0_1130
